# P7->P8: grid barrier replaced by release+arrive for all workgroups, wait+acquire only for the 32 top-k workgroups
# baseline (speedup 1.0000x reference)
; DEVINL int otid() { int t = threadIdx.x; asm volatile("" : "+v"(t)); return t; }
; DEVINL unsigned xb_ld(unsigned* p_) { return __hip_atomic_load(p_, __ATOMIC_RELAXED, __HIP_MEMORY_SCOPE_AGENT); }
; DEVINL unsigned xb_add(unsigned* p_, unsigned v) { return __hip_atomic_fetch_add(p_, v, __ATOMIC_RELAXED, __HIP_MEMORY_SCOPE_AGENT); }
; #define XB_SPIN(cond, bar) do { unsigned _sp = 0; while (cond) { __builtin_amdgcn_s_sleep(1); \
;     if ((++_sp & 255u) == 0u) { if (xb_ld(&(bar)[XB_TMO])) break; if (_sp > XB_SPIN_CAP) { atomicAdd(&(bar)[XB_TMO], 1u); break; } } } } while (0)
; DEVINL void phase8(const Params& p) {
;   char* ws = p.ws;
;   const int bid = blockIdx.x, nb = gridDim.x, tid = otid();
;   for (int pr = bid; pr < 32; pr += nb) {
;     const int b = pr >> 4, e = pr & 15;
; DEVINL void xcd_barrier(const XcdBarrier& b) {
;   asm volatile("s_waitcnt vmcnt(0)" ::: "memory");
;   __syncthreads();
;   if (threadIdx.x == 0) {
;     unsigned* bar = b.bar;
;     __builtin_amdgcn_s_waitcnt(0);
;     unsigned nloc = b.st[0], nx = b.st[1];
;     if (nloc == 0u) { xcd_barrier_complete(bar, b.x, nloc, nx); b.st[0] = nloc; b.st[1] = nx; }
;     const unsigned old = xb_add(&bar[XB_XSUB(b.x)], 1u);
;     const unsigned gen = old / nloc;
;     if (old + 1u == (gen + 1u) * nloc) {
;       __builtin_amdgcn_fence(__ATOMIC_RELEASE, "agent");
;       asm volatile("s_waitcnt vmcnt(0)" ::: "memory");
;       const unsigned og = xb_add(&bar[XB_TOP], 1u);
;       const unsigned tg = og / nx;
;       if (og + 1u == (tg + 1u) * nx) xb_add(&bar[XB_TOPGEN], 1u);
;       else XB_SPIN(xb_ld(&bar[XB_TOPGEN]) == tg, bar);
;       __builtin_amdgcn_fence(__ATOMIC_ACQUIRE, "agent");
;       xb_add(&bar[XB_XGEN(b.x)], 1u);
;       asm volatile("s_waitcnt vmcnt(0)" ::: "memory");
;     } else {
;       XB_SPIN(xb_ld(&bar[XB_XGEN(b.x)]) == gen, bar);
;       __builtin_amdgcn_fence(__ATOMIC_ACQUIRE, "agent");
;       asm volatile("s_waitcnt vmcnt(0)" ::: "memory");
;     }
;   }
;   __syncthreads();
.Lp7_end:
	s_mov_b64 exec, -1
	s_waitcnt vmcnt(0)
	s_barrier
	s_mov_b64 s[0:1], exec
	v_readlane_b32 s4, v254, 0
	v_readlane_b32 s5, v254, 1
	s_and_b64 s[4:5], s[0:1], s[4:5]
	s_mov_b64 exec, s[4:5]
	s_cbranch_execz .LBB0_794
	buffer_wbl2 sc1
	s_waitcnt vmcnt(0)
	v_mov_b32_e32 v0, 0
	v_mov_b32_e32 v1, 1
	global_atomic_add v0, v1, s[96:97] offset:8
	s_cmp_gt_i32 s2, 31
	s_cbranch_scc1 .Lp7_nowait
	s_mov_b32 s6, 0
.Lp7_spin:
	global_load_dword v2, v0, s[96:97] offset:8 sc1
	s_waitcnt vmcnt(0)
	v_readfirstlane_b32 s7, v2
	s_nop 3
	s_cmp_ge_u32 s7, 0x100
	s_cbranch_scc1 .Lp7_acq
	s_sleep 1
	s_add_u32 s6, s6, 1
	s_cmp_lt_u32 s6, 0x400000
	s_cbranch_scc1 .Lp7_spin
.Lp7_acq:
	buffer_inv sc1
	s_waitcnt vmcnt(0)
.Lp7_nowait:
.LBB0_794:
	s_or_b64 exec, exec, s[0:1]
	v_mov_b32_e32 v0, v189
	s_cmp_gt_i32 s2, 31
	s_waitcnt lgkmcnt(0)
	s_barrier
	s_cbranch_scc1 .LBB0_903
	s_add_u32 s22, s92, 0x1f680000
	s_addc_u32 s23, s93, 0
	v_and_b32_e32 v1, 63, v0
	s_add_u32 s24, s92, 0x1f690000
	v_cmp_eq_u32_e64 s[6:7], 0, v1
	s_addc_u32 s25, s93, 0
	v_ashrrev_i32_e32 v1, 31, v0
	s_add_u32 s26, s92, 0x21700000
	v_lshl_add_u64 v[2:3], v[0:1], 2, s[92:93]
	s_mov_b64 s[0:1], 0x1f600000
	v_cmp_gt_i32_e64 s[4:5], 40, v0
	v_mov_b32_e32 v4, 16
	v_lshl_add_u32 v5, v0, 2, 16
	s_addc_u32 s27, s93, 0
	v_lshl_add_u64 v[2:3], v[2:3], 0, s[0:1]
	v_mov_b32_e32 v1, 0
	s_add_i32 s3, 16, 0x78
	s_movk_i32 s38, 0x1ff
	s_movk_i32 s39, 0x200
	s_mov_b32 s28, s2
	s_branch .LBB0_797
